# t17 + attention QK phase: all 8 K-fragment ds_reads issued up front with counted lgkmcnt waits (3 step variants)
# baseline (speedup 1.0000x reference)
; #define LAS __attribute__((address_space(3)))
; #define MFMA32(a, b, c) __builtin_amdgcn_mfma_f32_32x32x16_bf16((a), (b), (c), 0, 0, 0)
; #define WG_BAR() do { asm volatile("s_waitcnt lgkmcnt(0)" ::: "memory"); __builtin_amdgcn_s_barrier(); asm volatile("" ::: "memory"); } while (0)
; #define ATT_DMA(t) do { const int t_ = (t) < NS ? (t) : NS - 1; const size_t ro_ = (size_t)TILE_ROW(t_) * ZC; LAS unsigned char* d_ = dk0 + ((t) % ATT_NB) * KV_BUF; \
;         __builtin_amdgcn_global_load_lds((const unsigned*)(gk + ro_), (LAS unsigned*)d_, 16, 0, 0); __builtin_amdgcn_global_load_lds((const unsigned*)(gv + ro_), (LAS unsigned*)(d_ + KV_TILE), 16, 0, 0); } while (0)
; template <class ScoreFn>
; __device__ __forceinline__ void attn_step(AttnState& st, const bf16x8 (&qf)[4], LAS unsigned char* kb, LAS unsigned char* vb, int lane, const ScoreFn& sf) {
;     const int r = lane & 31, h = lane >> 5;
;     f32x16 s0, s1;
; #pragma unroll
;     for (int i = 0; i < 16; ++i) { s0[i] = 0.f; s1[i] = 0.f; }
;     LAS unsigned char* kp = kb + r * KVP; const int kx = (h ^ (r & 7)) << 4;
; #pragma unroll
;     for (int ds = 0; ds < 4; ++ds) {
;         const bf16x8 k0 = *(const LAS bf16x8*)(kp + (kx ^ (ds << 5))), k1 = *(const LAS bf16x8*)(kp + 32 * KVP + (kx ^ (ds << 5)));
;         s0 = MFMA32(k0, qf[ds], s0); s1 = MFMA32(k1, qf[ds], s1);
;     }
;     float mt = NEG_BIG;
;     __builtin_amdgcn_sched_barrier(0);
; #pragma unroll
;     for (int i = 0; i < 16; ++i) { s0[i] = sf(s0[i], (i & 3) + 8 * (i >> 2), h, r); mt = fmaxf(mt, s0[i]); if ((i & 7) == 7) __builtin_amdgcn_sched_barrier(0); }
; #pragma unroll
;     for (int i = 0; i < 16; ++i) { s1[i] = sf(s1[i], 32 + (i & 3) + 8 * (i >> 2), h, r); mt = fmaxf(mt, s1[i]); if ((i & 7) == 7) __builtin_amdgcn_sched_barrier(0); }
;     mt = fmaxf(mt, __shfl_xor(mt, 32));
; template <bool ISB>
; __device__ __forceinline__ void attn_wg_item(Frame& F, int l, int idx) {
;     ...
;     for (int s = 0; s < NS; ++s) {
;         ATT_DMA(s + ATT_D);
;         asm volatile("s_waitcnt vmcnt(8)" ::: "memory");
;         WG_BAR();
;         LAS unsigned char* cur = ring + (s % ATT_NB) * KV_BUF;
;         if (s >= nloc) { ScorePlain sf; attn_step(st, qf, cur, cur + KV_TILE, lane, sf); }
.LBB0_581:
	s_mul_hi_u32 s1, s16, 0xaaaaaaab
	s_mul_hi_u32 s2, s13, 0xaaaaaaab
	s_lshr_b32 s1, s1, 2
	s_lshr_b32 s2, s2, 2
	s_mul_i32 s1, s1, 0x18000
	s_mul_i32 s2, s2, 0x18000
	v_readlane_b32 s3, v253, 15
	v_subrev_u32_e32 v6, s1, v88
	v_subrev_u32_e32 v7, s1, v90
	v_subrev_u32_e32 v8, s1, v91
	v_subrev_u32_e32 v9, s1, v92
	v_subrev_u32_e32 v10, s1, v93
	v_subrev_u32_e32 v11, s1, v94
	v_subrev_u32_e32 v12, s1, v95
	v_subrev_u32_e32 v13, s1, v96
	v_subrev_u32_e32 v14, s1, v97
	v_subrev_u32_e32 v15, s1, v98
	v_subrev_u32_e32 v16, s1, v99
	v_subrev_u32_e32 v17, s1, v100
	v_subrev_u32_e32 v20, s1, v101
	v_subrev_u32_e32 v21, s1, v102
	v_subrev_u32_e32 v22, s1, v103
	v_subrev_u32_e32 v23, s1, v104
	v_subrev_u32_e32 v128, s1, v105
	s_sub_i32 s8, s3, s2
	v_subrev_u32_e32 v130, s1, v106
	v_subrev_u32_e32 v131, s1, v107
	v_subrev_u32_e32 v132, s1, v108
	s_add_i32 s1, s16, 4
	s_cmp_lt_i32 s16, s11
	s_cselect_b64 s[2:3], -1, 0
	s_and_b64 vcc, s[2:3], exec
	s_cselect_b32 s1, s1, s12
	s_cmp_lt_i32 s1, s11
	s_cselect_b32 s2, 0, s11
	s_cselect_b32 s3, s10, 0x2000
	s_sub_i32 s1, s1, s2
	s_lshl_b32 s1, s1, 6
	s_add_i32 s1, s1, s3
	s_add_i32 s2, s15, s8
	v_mov_b32_e32 v84, v2
	v_mov_b32_e32 v85, v3
	s_add_i32 s8, s2, 0
	v_mad_i64_i32 v[2:3], s[2:3], s1, v249, v[50:51]
	s_add_i32 m0, s8, 0x10000
	v_lshl_add_u64 v[4:5], v[2:3], 0, s[18:19]
	global_load_lds_dwordx4 v[4:5], off
	v_lshl_add_u64 v[2:3], v[2:3], 0, s[20:21]
	s_add_i32 m0, s8, 0x12000
	v_mov_b32_e32 v82, v18
	global_load_lds_dwordx4 v[2:3], off
	s_waitcnt vmcnt(8)
	s_waitcnt lgkmcnt(0)
	s_barrier
	v_mov_b32_e32 v83, v19
	s_mov_b64 s[8:9], -1
	v_add3_u32 v126, s15, v23, v89
	v_add3_u32 v125, s15, v13, v89
	v_add3_u32 v127, s15, v22, v89
	v_add3_u32 v124, s15, v12, v89
	v_add3_u32 v122, s15, v21, v89
	v_add3_u32 v123, s15, v20, v89
	v_add3_u32 v119, s15, v11, v89
	v_add3_u32 v120, s15, v10, v89
	v_add3_u32 v117, s15, v17, v89
	v_add3_u32 v118, s15, v16, v89
	v_add3_u32 v115, s15, v9, v89
	v_add3_u32 v116, s15, v8, v89
	v_add3_u32 v113, s15, v15, v89
	v_add3_u32 v114, s15, v14, v89
	v_add3_u32 v111, s15, v7, v89
	v_add3_u32 v112, s15, v6, v89
	s_cbranch_vccnz .LBB0_583
	s_add_i32 s1, s15, 0
	v_add_u32_e32 v6, s1, v132
	v_add_u32_e32 v7, s1, v131
	v_add_u32_e32 v8, s1, v130
	v_add_u32_e32 v9, s1, v128
	ds_read_b128 v[2:5], v6
	ds_read_b128 v[22:25], v7
	ds_read_b128 v[26:29], v8
	ds_read_b128 v[30:33], v9
	ds_read_b128 v[18:21], v6 offset:4096
	ds_read_b128 v[134:137], v7 offset:4096
	ds_read_b128 v[138:141], v8 offset:4096
	ds_read_b128 v[142:145], v9 offset:4096
	s_waitcnt lgkmcnt(7)
	v_mfma_f32_32x32x16_bf16 v[2:17], v[2:5], v[34:37], 0
	s_waitcnt lgkmcnt(6)
	v_mfma_f32_32x32x16_bf16 v[2:17], v[22:25], v[38:41], v[2:17]
	s_waitcnt lgkmcnt(5)
	v_mfma_f32_32x32x16_bf16 v[2:17], v[26:29], v[42:45], v[2:17]
	s_waitcnt lgkmcnt(4)
	v_mfma_f32_32x32x16_bf16 v[2:17], v[30:33], v[46:49], v[2:17]
	s_waitcnt lgkmcnt(3)
	v_mfma_f32_32x32x16_bf16 v[18:33], v[18:21], v[34:37], 0
	s_waitcnt lgkmcnt(2)
	v_mfma_f32_32x32x16_bf16 v[18:33], v[134:137], v[38:41], v[18:33]
	s_waitcnt lgkmcnt(1)
	v_mfma_f32_32x32x16_bf16 v[18:33], v[138:141], v[42:45], v[18:33]
	s_waitcnt lgkmcnt(0)
	v_mfma_f32_32x32x16_bf16 v[18:33], v[142:145], v[46:49], v[18:33]
	s_nop 7
	v_mul_f32_e32 v66, 0x3e38aa3b, v2
	v_mul_f32_e32 v121, 0x3e38aa3b, v3
	s_mov_b32 s1, 0xf149f2ca
	v_max3_f32 v66, v66, s1, v121
	v_mul_f32_e32 v121, 0x3e38aa3b, v4
	v_mul_f32_e32 v129, 0x3e38aa3b, v5
	v_max3_f32 v66, v66, v121, v129
	v_mul_f32_e32 v121, 0x3e38aa3b, v6
	v_mul_f32_e32 v129, 0x3e38aa3b, v7
	v_max3_f32 v66, v66, v121, v129
	v_mul_f32_e32 v121, 0x3e38aa3b, v8
	v_mul_f32_e32 v129, 0x3e38aa3b, v9
	v_max3_f32 v66, v66, v121, v129
	v_mul_f32_e32 v121, 0x3e38aa3b, v10
	v_mul_f32_e32 v129, 0x3e38aa3b, v11
	v_max3_f32 v66, v66, v121, v129
	v_mul_f32_e32 v121, 0x3e38aa3b, v12
	v_mul_f32_e32 v129, 0x3e38aa3b, v13
	v_max3_f32 v66, v66, v121, v129
	v_mul_f32_e32 v121, 0x3e38aa3b, v14
	v_mul_f32_e32 v129, 0x3e38aa3b, v15
	v_max3_f32 v66, v66, v121, v129
	v_mul_f32_e32 v121, 0x3e38aa3b, v16
	v_mul_f32_e32 v129, 0x3e38aa3b, v17
	v_max3_f32 v66, v66, v121, v129
	v_mul_f32_e32 v121, 0x3e38aa3b, v18
	v_mul_f32_e32 v129, 0x3e38aa3b, v19
	v_max3_f32 v66, v66, v121, v129
	v_mul_f32_e32 v121, 0x3e38aa3b, v20
	v_mul_f32_e32 v129, 0x3e38aa3b, v21
	v_max3_f32 v66, v66, v121, v129
	v_mul_f32_e32 v121, 0x3e38aa3b, v22
	v_mul_f32_e32 v129, 0x3e38aa3b, v23
	v_max3_f32 v66, v66, v121, v129
	v_mul_f32_e32 v121, 0x3e38aa3b, v24
	v_mul_f32_e32 v129, 0x3e38aa3b, v25
	v_max3_f32 v66, v66, v121, v129
	v_mul_f32_e32 v121, 0x3e38aa3b, v26
	v_mul_f32_e32 v129, 0x3e38aa3b, v27
	v_max3_f32 v66, v66, v121, v129
	v_mul_f32_e32 v121, 0x3e38aa3b, v28
	v_mul_f32_e32 v129, 0x3e38aa3b, v29
	v_max3_f32 v66, v66, v121, v129
	v_mul_f32_e32 v121, 0x3e38aa3b, v30
	v_mul_f32_e32 v129, 0x3e38aa3b, v31
	v_max3_f32 v66, v66, v121, v129
	v_mul_f32_e32 v121, 0x3e38aa3b, v32
	v_mul_f32_e32 v129, 0x3e38aa3b, v33
	v_cmp_lt_i32_e32 vcc, v242, v241
	v_max3_f32 v66, v66, v121, v129
	s_nop 0
	v_cndmask_b32_e32 v121, v240, v242, vcc
	v_lshlrev_b32_e32 v121, 2, v121
	ds_bpermute_b32 v121, v121, v66
	s_waitcnt lgkmcnt(0)
; #define LAS __attribute__((address_space(3)))
; #define MFMA32(a, b, c) __builtin_amdgcn_mfma_f32_32x32x16_bf16((a), (b), (c), 0, 0, 0)
; __device__ __forceinline__ unsigned cvtpk(float lo, float hi) { return pg8::cvt_pk_bf16(lo, hi); }
; template <class ScoreFn>
; __device__ __forceinline__ void attn_step(AttnState& st, const bf16x8 (&qf)[4], LAS unsigned char* kb, LAS unsigned char* vb, int lane, const ScoreFn& sf) {
;     ...
;     mt = fmaxf(mt, __shfl_xor(mt, 32));
;     const float mn = fmaxf(st.m, mt), alpha = __builtin_amdgcn_exp2f(st.m - mn);
;     float ps = 0.f;
; #pragma unroll
;     for (int i = 0; i < 16; ++i) { s0[i] = __builtin_amdgcn_exp2f(s0[i] - mn); s1[i] = __builtin_amdgcn_exp2f(s1[i] - mn); ps += s0[i] + s1[i]; }
;     st.l = st.l * alpha + ps; st.m = mn;
; #pragma unroll
;     for (int i = 0; i < 16; ++i) { st.o0[i] *= alpha; st.o1[i] *= alpha; }
;     __builtin_amdgcn_sched_barrier(0);
;     v4u pw[4];
;     pw[0].x = cvtpk(s0[0], s0[1]); pw[0].y = cvtpk(s0[2], s0[3]); pw[0].z = cvtpk(s0[4], s0[5]); pw[0].w = cvtpk(s0[6], s0[7]);
;     pw[1].x = cvtpk(s0[8], s0[9]); pw[1].y = cvtpk(s0[10], s0[11]); pw[1].z = cvtpk(s0[12], s0[13]); pw[1].w = cvtpk(s0[14], s0[15]);
;     pw[2].x = cvtpk(s1[0], s1[1]); pw[2].y = cvtpk(s1[2], s1[3]); pw[2].z = cvtpk(s1[4], s1[5]); pw[2].w = cvtpk(s1[6], s1[7]);
;     pw[3].x = cvtpk(s1[8], s1[9]); pw[3].y = cvtpk(s1[10], s1[11]); pw[3].z = cvtpk(s1[12], s1[13]); pw[3].w = cvtpk(s1[14], s1[15]);
;     const int i16 = lane & 15, q = i16 >> 2, p = i16 & 3, dhalf = (lane >> 4) & 1;
;     LAS unsigned char* vrow = vb + (4 * h + q) * KVP + (p & 1) * 8;
;     LAS unsigned char* vp0 = vrow + (((2 * dhalf + (p >> 1)) ^ (4 * h + q)) << 4); LAS unsigned char* vp1 = vrow + (((4 + 2 * dhalf + (p >> 1)) ^ (4 * h + q)) << 4);
; #pragma unroll
;     for (int ks = 0; ks < 4; ++ks) {
;         const s16x4 l0 = tr_read(vp0 + (16 * ks) * KVP), h0 = tr_read(vp0 + (16 * ks + 8) * KVP);
;         const s16x4 l1 = tr_read(vp1 + (16 * ks) * KVP), h1 = tr_read(vp1 + (16 * ks + 8) * KVP);
;         const bf16x8 v0 = (bf16x8){l0[0], l0[1], l0[2], l0[3], h0[0], h0[1], h0[2], h0[3]};
;         const bf16x8 v1 = (bf16x8){l1[0], l1[1], l1[2], l1[3], h1[0], h1[1], h1[2], h1[3]};
;         const bf16x8 pf = __builtin_bit_cast(bf16x8, pw[ks]);
;         st.o0 = MFMA32(v0, pf, st.o0); st.o1 = MFMA32(v1, pf, st.o1);
;     }
	v_max3_f32 v121, v110, v66, v121
	v_fma_f32 v2, v2, s0, -v121
	v_exp_f32_e32 v133, v2
	v_fma_f32 v2, v18, s0, -v121
	v_exp_f32_e32 v165, v2
	v_fma_f32 v2, v3, s0, -v121
	v_exp_f32_e32 v66, v2
	v_fma_f32 v2, v19, s0, -v121
	v_exp_f32_e32 v142, v2
	v_add_f32_e32 v143, v165, v133
	v_pk_add_f32 v[2:3], v[142:143], v[66:67]
	s_nop 0
	v_pk_add_f32 v[136:137], v[2:3], v[2:3] op_sel_hi:[0,1]
	v_fma_f32 v2, v4, s0, -v121
	v_exp_f32_e32 v135, v2
	v_fma_f32 v2, v20, s0, -v121
	v_exp_f32_e32 v143, v2
	v_fma_f32 v2, v5, s0, -v121
	v_exp_f32_e32 v136, v2
	v_fma_f32 v2, v21, s0, -v121
	v_exp_f32_e32 v144, v2
	v_add_f32_e32 v145, v143, v135
	v_pk_add_f32 v[2:3], v[144:145], v[136:137]
	s_nop 0
	v_pk_add_f32 v[138:139], v[2:3], v[2:3] op_sel_hi:[0,1]
	v_fma_f32 v2, v6, s0, -v121
	v_exp_f32_e32 v137, v2
	v_fma_f32 v2, v22, s0, -v121
	v_exp_f32_e32 v145, v2
	v_fma_f32 v2, v7, s0, -v121
	v_exp_f32_e32 v138, v2
	v_fma_f32 v2, v23, s0, -v121
	v_exp_f32_e32 v146, v2
	v_add_f32_e32 v147, v145, v137
	v_pk_add_f32 v[2:3], v[146:147], v[138:139]
	s_nop 0
	v_pk_add_f32 v[140:141], v[2:3], v[2:3] op_sel_hi:[0,1]
	v_fma_f32 v2, v8, s0, -v121
	v_exp_f32_e32 v139, v2
	v_fma_f32 v2, v24, s0, -v121
	v_exp_f32_e32 v147, v2
	v_fma_f32 v2, v9, s0, -v121
	v_exp_f32_e32 v140, v2
	v_fma_f32 v2, v25, s0, -v121
	v_exp_f32_e32 v148, v2
	v_add_f32_e32 v149, v147, v139
	v_pk_add_f32 v[2:3], v[148:149], v[140:141]
	s_nop 0
	v_pk_add_f32 v[150:151], v[2:3], v[2:3] op_sel_hi:[0,1]
	v_fma_f32 v2, v10, s0, -v121
	v_exp_f32_e32 v141, v2
	v_fma_f32 v2, v26, s0, -v121
	v_exp_f32_e32 v149, v2
	v_fma_f32 v2, v11, s0, -v121
	v_exp_f32_e32 v150, v2
	v_fma_f32 v2, v27, s0, -v121
	v_exp_f32_e32 v152, v2
	v_add_f32_e32 v153, v149, v141
	v_pk_add_f32 v[2:3], v[152:153], v[150:151]
	s_nop 0
	v_pk_add_f32 v[154:155], v[2:3], v[2:3] op_sel_hi:[0,1]
	v_fma_f32 v2, v12, s0, -v121
	v_exp_f32_e32 v151, v2
	v_fma_f32 v2, v28, s0, -v121
	v_exp_f32_e32 v153, v2
	v_fma_f32 v2, v13, s0, -v121
	v_exp_f32_e32 v154, v2
	v_fma_f32 v2, v29, s0, -v121
	v_exp_f32_e32 v156, v2
	v_add_f32_e32 v157, v153, v151
	v_pk_add_f32 v[2:3], v[156:157], v[154:155]
	s_nop 0
	v_pk_add_f32 v[158:159], v[2:3], v[2:3] op_sel_hi:[0,1]
	v_fma_f32 v2, v14, s0, -v121
	v_exp_f32_e32 v155, v2
	v_fma_f32 v2, v30, s0, -v121
	v_exp_f32_e32 v157, v2
	v_fma_f32 v2, v15, s0, -v121
	v_exp_f32_e32 v158, v2
	v_fma_f32 v2, v31, s0, -v121
	v_exp_f32_e32 v160, v2
	v_add_f32_e32 v161, v157, v155
	v_pk_add_f32 v[2:3], v[160:161], v[158:159]
	s_nop 0
	v_pk_add_f32 v[162:163], v[2:3], v[2:3] op_sel_hi:[0,1]
	v_fma_f32 v2, v16, s0, -v121
	v_exp_f32_e32 v159, v2
	v_fma_f32 v2, v32, s0, -v121
	v_exp_f32_e32 v161, v2
	v_fma_f32 v2, v17, s0, -v121
	v_exp_f32_e32 v162, v2
	v_fma_f32 v2, v33, s0, -v121
	v_exp_f32_e32 v166, v2
	v_sub_f32_e32 v2, v110, v121
	v_exp_f32_e32 v18, v2
	v_add_f32_e32 v167, v161, v159
	v_pk_add_f32 v[2:3], v[166:167], v[162:163]
	v_pk_mul_f32 v[16:17], v[80:81], v[18:19] op_sel_hi:[1,0]
	v_add_f32_e32 v129, v2, v3
	v_fmac_f32_e32 v129, v109, v18
	v_pk_mul_f32 v[14:15], v[76:77], v[18:19] op_sel_hi:[1,0]
	v_pk_mul_f32 v[12:13], v[72:73], v[18:19] op_sel_hi:[1,0]
	v_pk_mul_f32 v[10:11], v[68:69], v[18:19] op_sel_hi:[1,0]
	v_pk_mul_f32 v[8:9], v[62:63], v[18:19] op_sel_hi:[1,0]
	v_pk_mul_f32 v[6:7], v[58:59], v[18:19] op_sel_hi:[1,0]
	v_pk_mul_f32 v[4:5], v[54:55], v[18:19] op_sel_hi:[1,0]
	v_pk_mul_f32 v[2:3], v[84:85], v[18:19] op_sel_hi:[1,0]
	v_pk_mul_f32 v[32:33], v[78:79], v[18:19] op_sel_hi:[1,0]
	v_pk_mul_f32 v[30:31], v[74:75], v[18:19] op_sel_hi:[1,0]
	v_pk_mul_f32 v[28:29], v[70:71], v[18:19] op_sel_hi:[1,0]
	v_pk_mul_f32 v[26:27], v[64:65], v[18:19] op_sel_hi:[1,0]
	v_pk_mul_f32 v[24:25], v[60:61], v[18:19] op_sel_hi:[1,0]
	v_pk_mul_f32 v[22:23], v[56:57], v[18:19] op_sel_hi:[1,0]
	v_pk_mul_f32 v[20:21], v[52:53], v[18:19] op_sel_hi:[1,0]
	v_pk_mul_f32 v[18:19], v[82:83], v[18:19] op_sel_hi:[1,0]
	v_cvt_pk_bf16_f32 v135, v135, v136
	v_cvt_pk_bf16_f32 v136, v137, v138
	v_cvt_pk_bf16_f32 v137, v139, v140
	v_cvt_pk_bf16_f32 v138, v141, v150
	v_cvt_pk_bf16_f32 v139, v151, v154
	v_cvt_pk_bf16_f32 v140, v155, v158
	v_cvt_pk_bf16_f32 v143, v143, v144
	v_cvt_pk_bf16_f32 v144, v145, v146
	v_cvt_pk_bf16_f32 v145, v147, v148
	v_cvt_pk_bf16_f32 v146, v149, v152
	v_cvt_pk_bf16_f32 v147, v153, v156
	v_cvt_pk_bf16_f32 v148, v157, v160
	ds_read_b64_tr_b16 v[150:151], v126
	ds_read_b64_tr_b16 v[152:153], v127
	ds_read_b64_tr_b16 v[154:155], v125
	ds_read_b64_tr_b16 v[156:157], v124
	v_cvt_pk_bf16_f32 v134, v133, v66
	v_cvt_pk_bf16_f32 v141, v159, v162
	v_cvt_pk_bf16_f32 v142, v165, v142
	s_waitcnt lgkmcnt(2)
	v_mfma_f32_32x32x16_bf16 v[2:17], v[150:153], v[134:137], v[2:17]
	v_cvt_pk_bf16_f32 v149, v161, v166
	s_mov_b64 s[8:9], 0
	s_waitcnt lgkmcnt(0)
	v_mfma_f32_32x32x16_bf16 v[18:33], v[154:157], v[134:137], v[18:33]
	ds_read_b64_tr_b16 v[134:135], v122
	ds_read_b64_tr_b16 v[136:137], v123
	ds_read_b64_tr_b16 v[150:151], v119
	ds_read_b64_tr_b16 v[152:153], v120
	s_waitcnt lgkmcnt(2)
	v_mfma_f32_32x32x16_bf16 v[2:17], v[134:137], v[138:141], v[2:17]
	s_waitcnt lgkmcnt(0)
	v_mfma_f32_32x32x16_bf16 v[18:33], v[150:153], v[138:141], v[18:33]
	ds_read_b64_tr_b16 v[134:135], v117
	ds_read_b64_tr_b16 v[136:137], v118
	ds_read_b64_tr_b16 v[138:139], v115
	ds_read_b64_tr_b16 v[140:141], v116
	s_waitcnt lgkmcnt(2)
	v_mfma_f32_32x32x16_bf16 v[2:17], v[134:137], v[142:145], v[2:17]
	s_waitcnt lgkmcnt(0)
	v_mfma_f32_32x32x16_bf16 v[18:33], v[138:141], v[142:145], v[18:33]
	ds_read_b64_tr_b16 v[134:135], v113
	ds_read_b64_tr_b16 v[136:137], v114
	ds_read_b64_tr_b16 v[138:139], v111
	ds_read_b64_tr_b16 v[140:141], v112
	s_waitcnt lgkmcnt(2)
	v_mfma_f32_32x32x16_bf16 v[2:17], v[134:137], v[146:149], v[2:17]
	s_waitcnt lgkmcnt(0)
	v_mfma_f32_32x32x16_bf16 v[18:33], v[138:141], v[146:149], v[18:33]
; #define LAS __attribute__((address_space(3)))
; #define MFMA32(a, b, c) __builtin_amdgcn_mfma_f32_32x32x16_bf16((a), (b), (c), 0, 0, 0)
; template <class ScoreFn>
; __device__ __forceinline__ void attn_step(AttnState& st, const bf16x8 (&qf)[4], LAS unsigned char* kb, LAS unsigned char* vb, int lane, const ScoreFn& sf) {
;     ...
;     LAS unsigned char* kp = kb + r * KVP; const int kx = (h ^ (r & 7)) << 4;
; #pragma unroll
;     for (int ds = 0; ds < 4; ++ds) {
;         const bf16x8 k0 = *(const LAS bf16x8*)(kp + (kx ^ (ds << 5))), k1 = *(const LAS bf16x8*)(kp + 32 * KVP + (kx ^ (ds << 5)));
;         s0 = MFMA32(k0, qf[ds], s0); s1 = MFMA32(k1, qf[ds], s1);
;     }
;     float mt = NEG_BIG;
;     __builtin_amdgcn_sched_barrier(0);
; #pragma unroll
;     for (int i = 0; i < 16; ++i) { s0[i] = sf(s0[i], (i & 3) + 8 * (i >> 2), h, r); mt = fmaxf(mt, s0[i]); if ((i & 7) == 7) __builtin_amdgcn_sched_barrier(0); }
; #pragma unroll
;     for (int i = 0; i < 16; ++i) { s1[i] = sf(s1[i], 32 + (i & 3) + 8 * (i >> 2), h, r); mt = fmaxf(mt, s1[i]); if ((i & 7) == 7) __builtin_amdgcn_sched_barrier(0); }
; template <bool ISB>
; __device__ __forceinline__ void attn_wg_item(Frame& F, int l, int idx) {
;     ...
;         else if (!ISB) { int dkv = krow_base + 64 * s - qrow0; asm volatile("" : "+v"(dkv)); ScoreWin sf{dkv}; attn_step(st, qf, cur, cur + KV_TILE, lane, sf); }
.LBB0_583:
	s_andn2_b64 vcc, exec, s[8:9]
	s_cbranch_vccnz .LBB0_585
	s_add_i32 s1, s15, 0
	v_mov_b32_e32 v66, s14
	s_nop 5
	v_add_u32_e32 v18, s1, v132
	v_add_u32_e32 v19, s1, v131
	v_add_u32_e32 v20, s1, v130
	v_add_u32_e32 v21, s1, v128
	ds_read_b128 v[2:5], v18
	ds_read_b128 v[10:13], v19
	ds_read_b128 v[14:17], v20
	ds_read_b128 v[142:145], v21
	ds_read_b128 v[6:9], v18 offset:4096
	ds_read_b128 v[130:133], v19 offset:4096
	ds_read_b128 v[134:137], v20 offset:4096
	ds_read_b128 v[138:141], v21 offset:4096
	s_waitcnt lgkmcnt(7)
	v_mfma_f32_32x32x16_bf16 v[18:33], v[2:5], v[34:37], 0
	s_waitcnt lgkmcnt(6)
	v_mfma_f32_32x32x16_bf16 v[18:33], v[10:13], v[38:41], v[18:33]
	s_waitcnt lgkmcnt(5)
	v_mfma_f32_32x32x16_bf16 v[18:33], v[14:17], v[42:45], v[18:33]
	s_waitcnt lgkmcnt(4)
	v_mfma_f32_32x32x16_bf16 v[18:33], v[142:145], v[46:49], v[18:33]
	s_waitcnt lgkmcnt(3)
	v_mfma_f32_32x32x16_bf16 v[2:17], v[6:9], v[34:37], 0
	s_waitcnt lgkmcnt(2)
	v_mfma_f32_32x32x16_bf16 v[2:17], v[130:133], v[38:41], v[2:17]
	s_waitcnt lgkmcnt(1)
	v_mfma_f32_32x32x16_bf16 v[2:17], v[134:137], v[42:45], v[2:17]
	s_waitcnt lgkmcnt(0)
	v_mfma_f32_32x32x16_bf16 v[2:17], v[138:141], v[46:49], v[2:17]
	v_add_u32_e32 v121, v86, v66
	s_nop 6
	v_mul_f32_e32 v18, 0x3e38aa3b, v18
	v_cmp_gt_u32_e32 vcc, s17, v121
	v_add_u32_e32 v128, 1, v121
	v_mul_f32_e32 v19, 0x3e38aa3b, v19
	v_cndmask_b32_e32 v18, v250, v18, vcc
	v_cmp_gt_u32_e32 vcc, s17, v128
	v_add_u32_e32 v129, 2, v121
	v_mul_f32_e32 v20, 0x3e38aa3b, v20
	v_cndmask_b32_e32 v19, v250, v19, vcc
	v_cmp_gt_u32_e32 vcc, s17, v129
	v_add_u32_e32 v129, 3, v121
	v_mul_f32_e32 v21, 0x3e38aa3b, v21
	v_cndmask_b32_e32 v20, v250, v20, vcc
	v_cmp_gt_u32_e32 vcc, s17, v129
	v_add_u32_e32 v129, 8, v121
	v_mul_f32_e32 v22, 0x3e38aa3b, v22
	v_cndmask_b32_e32 v21, v250, v21, vcc
	v_cmp_gt_u32_e32 vcc, s17, v129
	v_add_u32_e32 v129, 9, v121
	v_mul_f32_e32 v23, 0x3e38aa3b, v23
	v_cndmask_b32_e32 v22, v250, v22, vcc
	v_cmp_gt_u32_e32 vcc, s17, v129
	v_add_u32_e32 v129, 10, v121
	v_mul_f32_e32 v24, 0x3e38aa3b, v24
	v_cndmask_b32_e32 v23, v250, v23, vcc
	v_cmp_gt_u32_e32 vcc, s17, v129
	v_add_u32_e32 v129, 11, v121
	v_mul_f32_e32 v25, 0x3e38aa3b, v25
	v_cndmask_b32_e32 v24, v250, v24, vcc
	v_cmp_gt_u32_e32 vcc, s17, v129
	v_add_u32_e32 v129, 16, v121
	v_mul_f32_e32 v26, 0x3e38aa3b, v26
	v_cndmask_b32_e32 v25, v250, v25, vcc
	v_cmp_gt_u32_e32 vcc, s17, v129
	v_add_u32_e32 v129, 17, v121
	s_mov_b32 s1, 0xf149f2ca
	v_cndmask_b32_e32 v26, v250, v26, vcc
	v_mul_f32_e32 v27, 0x3e38aa3b, v27
	v_cmp_gt_u32_e32 vcc, s17, v129
	v_add_u32_e32 v129, 18, v121
	v_max3_f32 v128, v18, s1, v19
	v_cndmask_b32_e32 v27, v250, v27, vcc
	v_mul_f32_e32 v28, 0x3e38aa3b, v28
	v_cmp_gt_u32_e32 vcc, s17, v129
	v_add_u32_e32 v129, 19, v121
	v_max3_f32 v128, v128, v20, v21
	v_cndmask_b32_e32 v28, v250, v28, vcc
	v_mul_f32_e32 v29, 0x3e38aa3b, v29
	v_cmp_gt_u32_e32 vcc, s17, v129
	v_add_u32_e32 v129, 24, v121
	v_max3_f32 v128, v128, v22, v23
	v_cndmask_b32_e32 v29, v250, v29, vcc
	v_mul_f32_e32 v30, 0x3e38aa3b, v30
	v_cmp_gt_u32_e32 vcc, s17, v129
	v_add_u32_e32 v129, 25, v121
	v_max3_f32 v128, v128, v24, v25
	v_cndmask_b32_e32 v30, v250, v30, vcc
	v_mul_f32_e32 v31, 0x3e38aa3b, v31
	v_cmp_gt_u32_e32 vcc, s17, v129
	v_add_u32_e32 v129, 26, v121
	v_max3_f32 v128, v128, v26, v27
	v_cndmask_b32_e32 v31, v250, v31, vcc
	v_mul_f32_e32 v32, 0x3e38aa3b, v32
	v_cmp_gt_u32_e32 vcc, s17, v129
	v_add_u32_e32 v121, 27, v121
	v_max3_f32 v128, v128, v28, v29
	v_cndmask_b32_e32 v32, v250, v32, vcc
	v_mul_f32_e32 v33, 0x3e38aa3b, v33
	v_cmp_gt_u32_e32 vcc, s17, v121
	v_max3_f32 v128, v128, v30, v31
	v_add_u32_e32 v66, v87, v66
	v_cndmask_b32_e32 v33, v250, v33, vcc
	v_max3_f32 v121, v128, v32, v33
	v_mul_f32_e32 v2, 0x3e38aa3b, v2
	v_cmp_gt_u32_e32 vcc, s17, v66
	v_add_u32_e32 v128, 1, v66
	v_mul_f32_e32 v3, 0x3e38aa3b, v3
	v_cndmask_b32_e32 v2, v250, v2, vcc
	v_cmp_gt_u32_e32 vcc, s17, v128
	v_add_u32_e32 v128, 2, v66
	v_mul_f32_e32 v4, 0x3e38aa3b, v4
	v_cndmask_b32_e32 v3, v250, v3, vcc
	v_cmp_gt_u32_e32 vcc, s17, v128
	v_add_u32_e32 v128, 3, v66
	v_mul_f32_e32 v5, 0x3e38aa3b, v5
	v_cndmask_b32_e32 v4, v250, v4, vcc
	v_cmp_gt_u32_e32 vcc, s17, v128
	v_add_u32_e32 v128, 8, v66
	v_mul_f32_e32 v6, 0x3e38aa3b, v6
	v_cndmask_b32_e32 v5, v250, v5, vcc
	v_cmp_gt_u32_e32 vcc, s17, v128
	v_add_u32_e32 v128, 9, v66
	v_mul_f32_e32 v7, 0x3e38aa3b, v7
	v_cndmask_b32_e32 v6, v250, v6, vcc
	v_cmp_gt_u32_e32 vcc, s17, v128
	v_add_u32_e32 v128, 10, v66
	v_mul_f32_e32 v8, 0x3e38aa3b, v8
	v_cndmask_b32_e32 v7, v250, v7, vcc
	v_cmp_gt_u32_e32 vcc, s17, v128
	v_add_u32_e32 v128, 11, v66
	v_mul_f32_e32 v9, 0x3e38aa3b, v9
	v_cndmask_b32_e32 v8, v250, v8, vcc
	v_cmp_gt_u32_e32 vcc, s17, v128
	v_add_u32_e32 v128, 16, v66
	v_mul_f32_e32 v10, 0x3e38aa3b, v10
	v_cndmask_b32_e32 v9, v250, v9, vcc
	v_cmp_gt_u32_e32 vcc, s17, v128
	v_add_u32_e32 v128, 17, v66
	v_mul_f32_e32 v11, 0x3e38aa3b, v11
	v_cndmask_b32_e32 v10, v250, v10, vcc
	v_cmp_gt_u32_e32 vcc, s17, v128
	v_add_u32_e32 v128, 18, v66
	v_max3_f32 v121, v121, v2, v3
	v_cndmask_b32_e32 v11, v250, v11, vcc
	v_mul_f32_e32 v12, 0x3e38aa3b, v12
	v_cmp_gt_u32_e32 vcc, s17, v128
	v_add_u32_e32 v128, 19, v66
	v_max3_f32 v121, v121, v4, v5
	v_cndmask_b32_e32 v12, v250, v12, vcc
	v_mul_f32_e32 v13, 0x3e38aa3b, v13
	v_cmp_gt_u32_e32 vcc, s17, v128
	v_add_u32_e32 v128, 24, v66
	v_max3_f32 v121, v121, v6, v7
	v_cndmask_b32_e32 v13, v250, v13, vcc
	v_mul_f32_e32 v14, 0x3e38aa3b, v14
	v_cmp_gt_u32_e32 vcc, s17, v128
	v_add_u32_e32 v128, 25, v66
	v_max3_f32 v121, v121, v8, v9
	v_cndmask_b32_e32 v14, v250, v14, vcc
	v_mul_f32_e32 v15, 0x3e38aa3b, v15
	v_cmp_gt_u32_e32 vcc, s17, v128
	v_add_u32_e32 v128, 26, v66
	v_max3_f32 v121, v121, v10, v11
	v_cndmask_b32_e32 v15, v250, v15, vcc
	v_mul_f32_e32 v16, 0x3e38aa3b, v16
	v_cmp_gt_u32_e32 vcc, s17, v128
	v_add_u32_e32 v66, 27, v66
	v_max3_f32 v121, v121, v12, v13
	v_cndmask_b32_e32 v16, v250, v16, vcc
	v_mul_f32_e32 v17, 0x3e38aa3b, v17
	v_cmp_gt_u32_e32 vcc, s17, v66
	v_max3_f32 v121, v121, v14, v15
	s_nop 0
	v_cndmask_b32_e32 v17, v250, v17, vcc
	v_cmp_lt_i32_e32 vcc, v242, v241
	v_max3_f32 v66, v121, v16, v17
	s_nop 0
	v_cndmask_b32_e32 v121, v240, v242, vcc
	v_lshlrev_b32_e32 v121, 2, v121
	ds_bpermute_b32 v121, v121, v66
	s_waitcnt lgkmcnt(0)
; #define LAS __attribute__((address_space(3)))
; #define MFMA32(a, b, c) __builtin_amdgcn_mfma_f32_32x32x16_bf16((a), (b), (c), 0, 0, 0)
; __device__ __forceinline__ unsigned cvtpk(float lo, float hi) { return pg8::cvt_pk_bf16(lo, hi); }
; template <class ScoreFn>
; __device__ __forceinline__ void attn_step(AttnState& st, const bf16x8 (&qf)[4], LAS unsigned char* kb, LAS unsigned char* vb, int lane, const ScoreFn& sf) {
;     ...
;     mt = fmaxf(mt, __shfl_xor(mt, 32));
;     const float mn = fmaxf(st.m, mt), alpha = __builtin_amdgcn_exp2f(st.m - mn);
;     float ps = 0.f;
; #pragma unroll
;     for (int i = 0; i < 16; ++i) { s0[i] = __builtin_amdgcn_exp2f(s0[i] - mn); s1[i] = __builtin_amdgcn_exp2f(s1[i] - mn); ps += s0[i] + s1[i]; }
;     st.l = st.l * alpha + ps; st.m = mn;
; #pragma unroll
;     for (int i = 0; i < 16; ++i) { st.o0[i] *= alpha; st.o1[i] *= alpha; }
;     __builtin_amdgcn_sched_barrier(0);
;     v4u pw[4];
;     pw[0].x = cvtpk(s0[0], s0[1]); pw[0].y = cvtpk(s0[2], s0[3]); pw[0].z = cvtpk(s0[4], s0[5]); pw[0].w = cvtpk(s0[6], s0[7]);
;     pw[1].x = cvtpk(s0[8], s0[9]); pw[1].y = cvtpk(s0[10], s0[11]); pw[1].z = cvtpk(s0[12], s0[13]); pw[1].w = cvtpk(s0[14], s0[15]);
;     pw[2].x = cvtpk(s1[0], s1[1]); pw[2].y = cvtpk(s1[2], s1[3]); pw[2].z = cvtpk(s1[4], s1[5]); pw[2].w = cvtpk(s1[6], s1[7]);
;     pw[3].x = cvtpk(s1[8], s1[9]); pw[3].y = cvtpk(s1[10], s1[11]); pw[3].z = cvtpk(s1[12], s1[13]); pw[3].w = cvtpk(s1[14], s1[15]);
;     const int i16 = lane & 15, q = i16 >> 2, p = i16 & 3, dhalf = (lane >> 4) & 1;
;     LAS unsigned char* vrow = vb + (4 * h + q) * KVP + (p & 1) * 8;
;     LAS unsigned char* vp0 = vrow + (((2 * dhalf + (p >> 1)) ^ (4 * h + q)) << 4); LAS unsigned char* vp1 = vrow + (((4 + 2 * dhalf + (p >> 1)) ^ (4 * h + q)) << 4);
; #pragma unroll
;     for (int ks = 0; ks < 4; ++ks) {
;         const s16x4 l0 = tr_read(vp0 + (16 * ks) * KVP), h0 = tr_read(vp0 + (16 * ks + 8) * KVP);
;         const s16x4 l1 = tr_read(vp1 + (16 * ks) * KVP), h1 = tr_read(vp1 + (16 * ks + 8) * KVP);
;         const bf16x8 v0 = (bf16x8){l0[0], l0[1], l0[2], l0[3], h0[0], h0[1], h0[2], h0[3]};
;         const bf16x8 v1 = (bf16x8){l1[0], l1[1], l1[2], l1[3], h1[0], h1[1], h1[2], h1[3]};
;         const bf16x8 pf = __builtin_bit_cast(bf16x8, pw[ks]);
;         st.o0 = MFMA32(v0, pf, st.o0); st.o1 = MFMA32(v1, pf, st.o1);
;     }
	v_max3_f32 v121, v110, v66, v121
	v_sub_f32_e32 v2, v2, v121
	v_sub_f32_e32 v18, v18, v121
	v_exp_f32_e32 v159, v2
	v_sub_f32_e32 v2, v19, v121
	v_exp_f32_e32 v158, v18
	v_exp_f32_e32 v66, v2
	v_sub_f32_e32 v2, v3, v121
	v_exp_f32_e32 v128, v2
	v_add_f32_e32 v129, v159, v158
	v_pk_add_f32 v[2:3], v[128:129], v[66:67]
	s_nop 0
	v_pk_add_f32 v[130:131], v[2:3], v[2:3] op_sel_hi:[0,1]
	v_sub_f32_e32 v2, v20, v121
	v_exp_f32_e32 v160, v2
	v_sub_f32_e32 v2, v4, v121
	v_exp_f32_e32 v161, v2
	v_sub_f32_e32 v2, v21, v121
	v_exp_f32_e32 v130, v2
	v_sub_f32_e32 v2, v5, v121
	v_exp_f32_e32 v132, v2
	v_add_f32_e32 v133, v161, v160
	v_pk_add_f32 v[2:3], v[132:133], v[130:131]
	s_nop 0
	v_pk_add_f32 v[134:135], v[2:3], v[2:3] op_sel_hi:[0,1]
	v_sub_f32_e32 v2, v22, v121
	v_exp_f32_e32 v131, v2
	v_sub_f32_e32 v2, v6, v121
	v_exp_f32_e32 v133, v2
	v_sub_f32_e32 v2, v23, v121
	v_exp_f32_e32 v134, v2
	v_sub_f32_e32 v2, v7, v121
	v_exp_f32_e32 v136, v2
	v_add_f32_e32 v137, v133, v131
	v_pk_add_f32 v[2:3], v[136:137], v[134:135]
	s_nop 0
	v_pk_add_f32 v[138:139], v[2:3], v[2:3] op_sel_hi:[0,1]
	v_sub_f32_e32 v2, v24, v121
	v_exp_f32_e32 v135, v2
	v_sub_f32_e32 v2, v8, v121
	v_exp_f32_e32 v137, v2
	v_sub_f32_e32 v2, v25, v121
	v_exp_f32_e32 v138, v2
	v_sub_f32_e32 v2, v9, v121
	v_exp_f32_e32 v140, v2
	v_add_f32_e32 v141, v137, v135
	v_pk_add_f32 v[2:3], v[140:141], v[138:139]
	s_nop 0
	v_pk_add_f32 v[142:143], v[2:3], v[2:3] op_sel_hi:[0,1]
	v_sub_f32_e32 v2, v26, v121
	v_exp_f32_e32 v139, v2
	v_sub_f32_e32 v2, v10, v121
	v_exp_f32_e32 v141, v2
	v_sub_f32_e32 v2, v27, v121
	v_exp_f32_e32 v142, v2
	v_sub_f32_e32 v2, v11, v121
	v_exp_f32_e32 v144, v2
	v_add_f32_e32 v145, v141, v139
	v_pk_add_f32 v[2:3], v[144:145], v[142:143]
	s_nop 0
	v_pk_add_f32 v[146:147], v[2:3], v[2:3] op_sel_hi:[0,1]
	v_sub_f32_e32 v2, v28, v121
	v_exp_f32_e32 v143, v2
	v_sub_f32_e32 v2, v12, v121
	v_exp_f32_e32 v145, v2
	v_sub_f32_e32 v2, v29, v121
	v_exp_f32_e32 v146, v2
	v_sub_f32_e32 v2, v13, v121
	v_exp_f32_e32 v148, v2
	v_add_f32_e32 v149, v145, v143
	v_pk_add_f32 v[2:3], v[148:149], v[146:147]
	s_nop 0
	v_pk_add_f32 v[150:151], v[2:3], v[2:3] op_sel_hi:[0,1]
	v_sub_f32_e32 v2, v30, v121
	v_exp_f32_e32 v147, v2
	v_sub_f32_e32 v2, v14, v121
	v_exp_f32_e32 v149, v2
	v_sub_f32_e32 v2, v31, v121
	v_exp_f32_e32 v150, v2
	v_sub_f32_e32 v2, v15, v121
	v_exp_f32_e32 v152, v2
	v_add_f32_e32 v153, v149, v147
	v_pk_add_f32 v[2:3], v[152:153], v[150:151]
	s_nop 0
	v_pk_add_f32 v[154:155], v[2:3], v[2:3] op_sel_hi:[0,1]
	v_sub_f32_e32 v2, v32, v121
	v_exp_f32_e32 v151, v2
	v_sub_f32_e32 v2, v16, v121
	v_exp_f32_e32 v153, v2
	v_sub_f32_e32 v2, v33, v121
	v_exp_f32_e32 v154, v2
	v_sub_f32_e32 v2, v17, v121
	v_exp_f32_e32 v156, v2
	v_sub_f32_e32 v2, v110, v121
	v_exp_f32_e32 v18, v2
	v_add_f32_e32 v157, v153, v151
	v_pk_add_f32 v[2:3], v[156:157], v[154:155]
	v_pk_mul_f32 v[16:17], v[80:81], v[18:19] op_sel_hi:[1,0]
	v_add_f32_e32 v129, v2, v3
	v_fmac_f32_e32 v129, v109, v18
	v_pk_mul_f32 v[14:15], v[76:77], v[18:19] op_sel_hi:[1,0]
	v_pk_mul_f32 v[12:13], v[72:73], v[18:19] op_sel_hi:[1,0]
	v_pk_mul_f32 v[10:11], v[68:69], v[18:19] op_sel_hi:[1,0]
	v_pk_mul_f32 v[8:9], v[62:63], v[18:19] op_sel_hi:[1,0]
	v_pk_mul_f32 v[6:7], v[58:59], v[18:19] op_sel_hi:[1,0]
	v_pk_mul_f32 v[4:5], v[54:55], v[18:19] op_sel_hi:[1,0]
	v_pk_mul_f32 v[2:3], v[84:85], v[18:19] op_sel_hi:[1,0]
	v_pk_mul_f32 v[32:33], v[78:79], v[18:19] op_sel_hi:[1,0]
	v_pk_mul_f32 v[30:31], v[74:75], v[18:19] op_sel_hi:[1,0]
	v_pk_mul_f32 v[28:29], v[70:71], v[18:19] op_sel_hi:[1,0]
	v_pk_mul_f32 v[26:27], v[64:65], v[18:19] op_sel_hi:[1,0]
	v_pk_mul_f32 v[24:25], v[60:61], v[18:19] op_sel_hi:[1,0]
	v_pk_mul_f32 v[22:23], v[56:57], v[18:19] op_sel_hi:[1,0]
	v_pk_mul_f32 v[20:21], v[52:53], v[18:19] op_sel_hi:[1,0]
	v_pk_mul_f32 v[18:19], v[82:83], v[18:19] op_sel_hi:[1,0]
	ds_read_b64_tr_b16 v[72:73], v126
	ds_read_b64_tr_b16 v[74:75], v127
	ds_read_b64_tr_b16 v[76:77], v125
	ds_read_b64_tr_b16 v[78:79], v124
	v_cvt_pk_bf16_f32 v52, v158, v66
	v_cvt_pk_bf16_f32 v53, v160, v130
	v_cvt_pk_bf16_f32 v54, v131, v134
	v_cvt_pk_bf16_f32 v55, v135, v138
	v_cvt_pk_bf16_f32 v56, v139, v142
	v_cvt_pk_bf16_f32 v57, v143, v146
	s_waitcnt lgkmcnt(2)
	v_mfma_f32_32x32x16_bf16 v[2:17], v[72:75], v[52:55], v[2:17]
	v_cvt_pk_bf16_f32 v58, v147, v150
	v_cvt_pk_bf16_f32 v59, v151, v154
	v_cvt_pk_bf16_f32 v60, v159, v128
	v_cvt_pk_bf16_f32 v61, v161, v132
	v_cvt_pk_bf16_f32 v62, v133, v136
	v_cvt_pk_bf16_f32 v63, v137, v140
	v_cvt_pk_bf16_f32 v68, v141, v144
	s_waitcnt lgkmcnt(0)
	v_mfma_f32_32x32x16_bf16 v[18:33], v[76:79], v[52:55], v[18:33]
	ds_read_b64_tr_b16 v[52:53], v122
	ds_read_b64_tr_b16 v[54:55], v123
	ds_read_b64_tr_b16 v[72:73], v119
	ds_read_b64_tr_b16 v[74:75], v120
	v_cvt_pk_bf16_f32 v69, v145, v148
	v_cvt_pk_bf16_f32 v70, v149, v152
	v_cvt_pk_bf16_f32 v71, v153, v156
	s_waitcnt lgkmcnt(2)
	v_mfma_f32_32x32x16_bf16 v[2:17], v[52:55], v[56:59], v[2:17]
	s_waitcnt lgkmcnt(0)
	v_mfma_f32_32x32x16_bf16 v[18:33], v[72:75], v[56:59], v[18:33]
	ds_read_b64_tr_b16 v[52:53], v117
	ds_read_b64_tr_b16 v[54:55], v118
	ds_read_b64_tr_b16 v[56:57], v115
	ds_read_b64_tr_b16 v[58:59], v116
	s_waitcnt lgkmcnt(2)
	v_mfma_f32_32x32x16_bf16 v[2:17], v[52:55], v[60:63], v[2:17]
	s_waitcnt lgkmcnt(0)
	v_mfma_f32_32x32x16_bf16 v[18:33], v[56:59], v[60:63], v[18:33]
	ds_read_b64_tr_b16 v[52:53], v113
	ds_read_b64_tr_b16 v[54:55], v114
	ds_read_b64_tr_b16 v[56:57], v111
	ds_read_b64_tr_b16 v[58:59], v112
	s_waitcnt lgkmcnt(2)
	v_mfma_f32_32x32x16_bf16 v[2:17], v[52:55], v[68:71], v[2:17]
	s_waitcnt lgkmcnt(0)
	v_mfma_f32_32x32x16_bf16 v[18:33], v[56:59], v[68:71], v[18:33]

; #define LAS __attribute__((address_space(3)))
; #define MFMA32(a, b, c) __builtin_amdgcn_mfma_f32_32x32x16_bf16((a), (b), (c), 0, 0, 0)
; #define WG_BAR() do { asm volatile("s_waitcnt lgkmcnt(0)" ::: "memory"); __builtin_amdgcn_s_barrier(); asm volatile("" ::: "memory"); } while (0)
; #define ATT_DMA(t) do { const int t_ = (t) < NS ? (t) : NS - 1; const size_t ro_ = (size_t)TILE_ROW(t_) * ZC; LAS unsigned char* d_ = dk0 + ((t) % ATT_NB) * KV_BUF; \
;         __builtin_amdgcn_global_load_lds((const unsigned*)(gk + ro_), (LAS unsigned*)d_, 16, 0, 0); __builtin_amdgcn_global_load_lds((const unsigned*)(gv + ro_), (LAS unsigned*)(d_ + KV_TILE), 16, 0, 0); } while (0)
; template <class ScoreFn>
; __device__ __forceinline__ void attn_step(AttnState& st, const bf16x8 (&qf)[4], LAS unsigned char* kb, LAS unsigned char* vb, int lane, const ScoreFn& sf) {
;     ...
;     LAS unsigned char* kp = kb + r * KVP; const int kx = (h ^ (r & 7)) << 4;
; #pragma unroll
;     for (int ds = 0; ds < 4; ++ds) {
;         const bf16x8 k0 = *(const LAS bf16x8*)(kp + (kx ^ (ds << 5))), k1 = *(const LAS bf16x8*)(kp + 32 * KVP + (kx ^ (ds << 5)));
;         s0 = MFMA32(k0, qf[ds], s0); s1 = MFMA32(k1, qf[ds], s1);
;     }
;     float mt = NEG_BIG;
;     __builtin_amdgcn_sched_barrier(0);
; #pragma unroll
;     for (int i = 0; i < 16; ++i) { s0[i] = sf(s0[i], (i & 3) + 8 * (i >> 2), h, r); mt = fmaxf(mt, s0[i]); if ((i & 7) == 7) __builtin_amdgcn_sched_barrier(0); }
; #pragma unroll
;     for (int i = 0; i < 16; ++i) { s1[i] = sf(s1[i], 32 + (i & 3) + 8 * (i >> 2), h, r); mt = fmaxf(mt, s1[i]); if ((i & 7) == 7) __builtin_amdgcn_sched_barrier(0); }
;     mt = fmaxf(mt, __shfl_xor(mt, 32));
; template <bool ISB>
; __device__ __forceinline__ void attn_wg_item(Frame& F, int l, int idx) {
;     ...
;     for (int s = 0; s < NS; ++s) {
;         ATT_DMA(s + ATT_D);
;         asm volatile("s_waitcnt vmcnt(8)" ::: "memory");
;         WG_BAR();
;         LAS unsigned char* cur = ring + (s % ATT_NB) * KV_BUF;
;         if (s >= nloc) { ScorePlain sf; attn_step(st, qf, cur, cur + KV_TILE, lane, sf); }
.LBB0_618:
	s_mul_hi_u32 s1, s80, 0xaaaaaaab
	s_lshr_b32 s1, s1, 2
	s_mul_i32 s1, s1, 0x18000
	v_readlane_b32 s2, v253, 14
	s_sub_i32 s74, s2, s1
	v_readlane_b32 s2, v253, 16
	s_sub_i32 s1, s2, s1
	s_mul_hi_u32 s2, s82, 0xaaaaaaab
	s_lshr_b32 s2, s2, 2
	s_add_i32 s75, s82, 4
	s_mul_i32 s2, s2, 0x18000
	s_cmp_lt_i32 s82, s78
	v_subrev_u32_e32 v139, s2, v96
	v_subrev_u32_e32 v138, s2, v97
	v_subrev_u32_e32 v137, s2, v98
	v_subrev_u32_e32 v136, s2, v99
	v_subrev_u32_e32 v134, s2, v100
	v_subrev_u32_e32 v133, s2, v102
	v_subrev_u32_e32 v129, s2, v103
	v_subrev_u32_e32 v128, s2, v104
	v_subrev_u32_e32 v125, s2, v105
	v_subrev_u32_e32 v124, s2, v106
	v_subrev_u32_e32 v121, s2, v107
	v_subrev_u32_e32 v120, s2, v108
	v_subrev_u32_e32 v118, s2, v110
	v_subrev_u32_e32 v119, s2, v111
	v_subrev_u32_e32 v122, s2, v112
	v_subrev_u32_e32 v123, s2, v113
	v_subrev_u32_e32 v126, s2, v114
	v_subrev_u32_e32 v127, s2, v115
	v_subrev_u32_e32 v132, s2, v116
	v_subrev_u32_e32 v135, s2, v117
	s_cselect_b64 s[2:3], -1, 0
	s_and_b64 vcc, s[2:3], exec
	s_cselect_b32 s2, s75, s79
	s_cmp_lt_i32 s2, s78
	s_cselect_b32 s3, 0, s78
	s_cselect_b32 s75, s77, 0x2000
	s_sub_i32 s2, s2, s3
	s_lshl_b32 s2, s2, 6
	s_add_i32 s2, s2, s75
	s_add_i32 s3, s81, s74
	s_add_i32 m0, s3, 0
	v_mad_i64_i32 v[34:35], s[2:3], s2, v249, v[92:93]
	v_lshl_add_u64 v[36:37], v[34:35], 0, s[86:87]
	s_add_i32 s1, s81, s1
	global_load_lds_dwordx4 v[36:37], off
	v_lshl_add_u64 v[34:35], v[34:35], 0, s[96:97]
	s_add_i32 m0, s1, 0
	s_mov_b64 s[74:75], -1
	global_load_lds_dwordx4 v[34:35], off
	s_waitcnt vmcnt(8)
	s_waitcnt lgkmcnt(0)
	s_barrier
	s_cbranch_vccnz .LBB0_620
	s_add_i32 s1, s81, 0
	v_add_u32_e32 v38, s1, v139
	v_add_u32_e32 v39, s1, v138
	v_add_u32_e32 v40, s1, v137
	v_add_u32_e32 v41, s1, v136
	ds_read_b128 v[34:37], v38
	ds_read_b128 v[54:57], v39
	ds_read_b128 v[58:61], v40
	ds_read_b128 v[62:65], v41
	ds_read_b128 v[50:53], v38 offset:4096
	ds_read_b128 v[84:87], v39 offset:4096
	ds_read_b128 v[88:91], v40 offset:4096
	ds_read_b128 v[140:143], v41 offset:4096
	s_waitcnt lgkmcnt(7)
	v_mfma_f32_32x32x16_bf16 v[34:49], v[34:37], v[68:71], 0
	s_waitcnt lgkmcnt(6)
	v_mfma_f32_32x32x16_bf16 v[34:49], v[54:57], v[72:75], v[34:49]
	s_waitcnt lgkmcnt(5)
	v_mfma_f32_32x32x16_bf16 v[34:49], v[58:61], v[76:79], v[34:49]
	s_waitcnt lgkmcnt(4)
	v_mfma_f32_32x32x16_bf16 v[34:49], v[62:65], v[80:83], v[34:49]
	s_waitcnt lgkmcnt(3)
	v_mfma_f32_32x32x16_bf16 v[50:65], v[50:53], v[68:71], 0
	s_waitcnt lgkmcnt(2)
	v_mfma_f32_32x32x16_bf16 v[50:65], v[84:87], v[72:75], v[50:65]
	s_waitcnt lgkmcnt(1)
	v_mfma_f32_32x32x16_bf16 v[50:65], v[88:91], v[76:79], v[50:65]
	s_waitcnt lgkmcnt(0)
	v_mfma_f32_32x32x16_bf16 v[50:65], v[140:143], v[80:83], v[50:65]
	s_nop 7
	v_mul_f32_e32 v66, 0x3e38aa3b, v34
	v_mul_f32_e32 v84, 0x3e38aa3b, v35
	s_mov_b32 s1, 0xf149f2ca
	v_max3_f32 v66, v66, s1, v84
	v_mul_f32_e32 v84, 0x3e38aa3b, v36
	v_mul_f32_e32 v85, 0x3e38aa3b, v37
	v_max3_f32 v66, v66, v84, v85
	v_mul_f32_e32 v84, 0x3e38aa3b, v38
	v_mul_f32_e32 v85, 0x3e38aa3b, v39
	v_max3_f32 v66, v66, v84, v85
	v_mul_f32_e32 v84, 0x3e38aa3b, v40
	v_mul_f32_e32 v85, 0x3e38aa3b, v41
	v_max3_f32 v66, v66, v84, v85
	v_mul_f32_e32 v84, 0x3e38aa3b, v42
	v_mul_f32_e32 v85, 0x3e38aa3b, v43
	v_max3_f32 v66, v66, v84, v85
	v_mul_f32_e32 v84, 0x3e38aa3b, v44
	v_mul_f32_e32 v85, 0x3e38aa3b, v45
	v_max3_f32 v66, v66, v84, v85
	v_mul_f32_e32 v84, 0x3e38aa3b, v46
	v_mul_f32_e32 v85, 0x3e38aa3b, v47
	v_max3_f32 v66, v66, v84, v85
	v_mul_f32_e32 v84, 0x3e38aa3b, v48
	v_mul_f32_e32 v85, 0x3e38aa3b, v49
	v_max3_f32 v66, v66, v84, v85
	v_mul_f32_e32 v84, 0x3e38aa3b, v50
	v_mul_f32_e32 v85, 0x3e38aa3b, v51
	v_max3_f32 v66, v66, v84, v85
	v_mul_f32_e32 v84, 0x3e38aa3b, v52
	v_mul_f32_e32 v85, 0x3e38aa3b, v53
	v_max3_f32 v66, v66, v84, v85
	v_mul_f32_e32 v84, 0x3e38aa3b, v54
	v_mul_f32_e32 v85, 0x3e38aa3b, v55
	v_max3_f32 v66, v66, v84, v85
	v_mul_f32_e32 v84, 0x3e38aa3b, v56
	v_mul_f32_e32 v85, 0x3e38aa3b, v57
	v_max3_f32 v66, v66, v84, v85
	v_mul_f32_e32 v84, 0x3e38aa3b, v58
	v_mul_f32_e32 v85, 0x3e38aa3b, v59
	v_max3_f32 v66, v66, v84, v85
	v_mul_f32_e32 v84, 0x3e38aa3b, v60
	v_mul_f32_e32 v85, 0x3e38aa3b, v61
	v_max3_f32 v66, v66, v84, v85
	v_mul_f32_e32 v84, 0x3e38aa3b, v62
	v_mul_f32_e32 v85, 0x3e38aa3b, v63
	v_max3_f32 v66, v66, v84, v85
	v_mul_f32_e32 v84, 0x3e38aa3b, v64
	v_mul_f32_e32 v85, 0x3e38aa3b, v65
	v_cmp_lt_i32_e32 vcc, v242, v241
	v_max3_f32 v66, v66, v84, v85
	s_nop 0
	v_cndmask_b32_e32 v84, v240, v242, vcc
	v_lshlrev_b32_e32 v84, 2, v84
	ds_bpermute_b32 v84, v84, v66
	s_waitcnt lgkmcnt(0)
; #define LAS __attribute__((address_space(3)))
; #define MFMA32(a, b, c) __builtin_amdgcn_mfma_f32_32x32x16_bf16((a), (b), (c), 0, 0, 0)
; __device__ __forceinline__ unsigned cvtpk(float lo, float hi) { return pg8::cvt_pk_bf16(lo, hi); }
; template <class ScoreFn>
; __device__ __forceinline__ void attn_step(AttnState& st, const bf16x8 (&qf)[4], LAS unsigned char* kb, LAS unsigned char* vb, int lane, const ScoreFn& sf) {
;     ...
;     mt = fmaxf(mt, __shfl_xor(mt, 32));
;     const float mn = fmaxf(st.m, mt), alpha = __builtin_amdgcn_exp2f(st.m - mn);
;     float ps = 0.f;
; #pragma unroll
;     for (int i = 0; i < 16; ++i) { s0[i] = __builtin_amdgcn_exp2f(s0[i] - mn); s1[i] = __builtin_amdgcn_exp2f(s1[i] - mn); ps += s0[i] + s1[i]; }
;     st.l = st.l * alpha + ps; st.m = mn;
; #pragma unroll
;     for (int i = 0; i < 16; ++i) { st.o0[i] *= alpha; st.o1[i] *= alpha; }
;     __builtin_amdgcn_sched_barrier(0);
;     v4u pw[4];
;     pw[0].x = cvtpk(s0[0], s0[1]); pw[0].y = cvtpk(s0[2], s0[3]); pw[0].z = cvtpk(s0[4], s0[5]); pw[0].w = cvtpk(s0[6], s0[7]);
;     pw[1].x = cvtpk(s0[8], s0[9]); pw[1].y = cvtpk(s0[10], s0[11]); pw[1].z = cvtpk(s0[12], s0[13]); pw[1].w = cvtpk(s0[14], s0[15]);
;     pw[2].x = cvtpk(s1[0], s1[1]); pw[2].y = cvtpk(s1[2], s1[3]); pw[2].z = cvtpk(s1[4], s1[5]); pw[2].w = cvtpk(s1[6], s1[7]);
;     pw[3].x = cvtpk(s1[8], s1[9]); pw[3].y = cvtpk(s1[10], s1[11]); pw[3].z = cvtpk(s1[12], s1[13]); pw[3].w = cvtpk(s1[14], s1[15]);
;     const int i16 = lane & 15, q = i16 >> 2, p = i16 & 3, dhalf = (lane >> 4) & 1;
;     LAS unsigned char* vrow = vb + (4 * h + q) * KVP + (p & 1) * 8;
;     LAS unsigned char* vp0 = vrow + (((2 * dhalf + (p >> 1)) ^ (4 * h + q)) << 4); LAS unsigned char* vp1 = vrow + (((4 + 2 * dhalf + (p >> 1)) ^ (4 * h + q)) << 4);
; #pragma unroll
;     for (int ks = 0; ks < 4; ++ks) {
;         const s16x4 l0 = tr_read(vp0 + (16 * ks) * KVP), h0 = tr_read(vp0 + (16 * ks + 8) * KVP);
;         const s16x4 l1 = tr_read(vp1 + (16 * ks) * KVP), h1 = tr_read(vp1 + (16 * ks + 8) * KVP);
;         const bf16x8 v0 = (bf16x8){l0[0], l0[1], l0[2], l0[3], h0[0], h0[1], h0[2], h0[3]};
;         const bf16x8 v1 = (bf16x8){l1[0], l1[1], l1[2], l1[3], h1[0], h1[1], h1[2], h1[3]};
;         const bf16x8 pf = __builtin_bit_cast(bf16x8, pw[ks]);
;         st.o0 = MFMA32(v0, pf, st.o0); st.o1 = MFMA32(v1, pf, st.o1);
;     }
	v_max3_f32 v140, v131, v66, v84
	v_fma_f32 v34, v34, s0, -v140
	v_exp_f32_e32 v142, v34
	v_fma_f32 v34, v50, s0, -v140
	v_exp_f32_e32 v165, v34
	v_fma_f32 v34, v35, s0, -v140
	v_exp_f32_e32 v66, v34
	v_fma_f32 v34, v51, s0, -v140
	v_exp_f32_e32 v84, v34
	v_add_f32_e32 v85, v165, v142
	v_pk_add_f32 v[34:35], v[84:85], v[66:67]
	s_nop 0
	v_pk_add_f32 v[86:87], v[34:35], v[34:35] op_sel_hi:[0,1]
	v_fma_f32 v34, v36, s0, -v140
	v_exp_f32_e32 v85, v34
	v_fma_f32 v34, v52, s0, -v140
	v_exp_f32_e32 v170, v34
	v_fma_f32 v34, v37, s0, -v140
	v_exp_f32_e32 v86, v34
	v_fma_f32 v34, v53, s0, -v140
	v_exp_f32_e32 v90, v34
	v_add_f32_e32 v91, v170, v85
	v_pk_add_f32 v[34:35], v[90:91], v[86:87]
	s_nop 0
	v_pk_add_f32 v[88:89], v[34:35], v[34:35] op_sel_hi:[0,1]
	v_fma_f32 v34, v38, s0, -v140
	v_exp_f32_e32 v87, v34
	v_fma_f32 v34, v54, s0, -v140
	v_exp_f32_e32 v91, v34
	v_fma_f32 v34, v39, s0, -v140
	v_exp_f32_e32 v88, v34
	v_fma_f32 v34, v55, s0, -v140
	v_exp_f32_e32 v150, v34
	v_add_f32_e32 v151, v91, v87
	v_pk_add_f32 v[34:35], v[150:151], v[88:89]
	s_nop 0
	v_pk_add_f32 v[146:147], v[34:35], v[34:35] op_sel_hi:[0,1]
	v_fma_f32 v34, v40, s0, -v140
	v_exp_f32_e32 v89, v34
	v_fma_f32 v34, v56, s0, -v140
	v_exp_f32_e32 v151, v34
	v_fma_f32 v34, v41, s0, -v140
	v_exp_f32_e32 v146, v34
	v_fma_f32 v34, v57, s0, -v140
	v_exp_f32_e32 v152, v34
	v_add_f32_e32 v153, v151, v89
	v_pk_add_f32 v[34:35], v[152:153], v[146:147]
	s_nop 0
	v_pk_add_f32 v[148:149], v[34:35], v[34:35] op_sel_hi:[0,1]
	v_fma_f32 v34, v42, s0, -v140
	v_exp_f32_e32 v147, v34
	v_fma_f32 v34, v58, s0, -v140
	v_exp_f32_e32 v153, v34
	v_fma_f32 v34, v43, s0, -v140
	v_exp_f32_e32 v148, v34
	v_fma_f32 v34, v59, s0, -v140
	v_exp_f32_e32 v154, v34
	v_add_f32_e32 v155, v153, v147
	v_pk_add_f32 v[34:35], v[154:155], v[148:149]
	s_nop 0
	v_pk_add_f32 v[156:157], v[34:35], v[34:35] op_sel_hi:[0,1]
	v_fma_f32 v34, v44, s0, -v140
	v_exp_f32_e32 v149, v34
	v_fma_f32 v34, v60, s0, -v140
	v_exp_f32_e32 v155, v34
	v_fma_f32 v34, v45, s0, -v140
	v_exp_f32_e32 v156, v34
	v_fma_f32 v34, v61, s0, -v140
	v_exp_f32_e32 v158, v34
	v_add_f32_e32 v159, v155, v149
	v_pk_add_f32 v[34:35], v[158:159], v[156:157]
	s_nop 0
	v_pk_add_f32 v[160:161], v[34:35], v[34:35] op_sel_hi:[0,1]
	v_fma_f32 v34, v46, s0, -v140
	v_exp_f32_e32 v157, v34
	v_fma_f32 v34, v62, s0, -v140
	v_exp_f32_e32 v159, v34
	v_fma_f32 v34, v47, s0, -v140
	v_exp_f32_e32 v160, v34
	v_fma_f32 v34, v63, s0, -v140
	v_exp_f32_e32 v162, v34
	v_add_f32_e32 v163, v159, v157
	v_pk_add_f32 v[34:35], v[162:163], v[160:161]
	s_nop 0
	v_pk_add_f32 v[166:167], v[34:35], v[34:35] op_sel_hi:[0,1]
	v_fma_f32 v34, v48, s0, -v140
	v_exp_f32_e32 v161, v34
	v_fma_f32 v34, v64, s0, -v140
	v_exp_f32_e32 v163, v34
	v_fma_f32 v34, v49, s0, -v140
	v_exp_f32_e32 v166, v34
	v_fma_f32 v34, v65, s0, -v140
	v_exp_f32_e32 v168, v34
	v_sub_f32_e32 v34, v131, v140
	v_exp_f32_e32 v50, v34
	v_add_f32_e32 v169, v163, v161
	v_pk_add_f32 v[34:35], v[168:169], v[166:167]
	v_pk_mul_f32 v[48:49], v[32:33], v[50:51] op_sel_hi:[1,0]
	v_add_f32_e32 v141, v34, v35
	v_fmac_f32_e32 v141, v130, v50
	v_pk_mul_f32 v[46:47], v[30:31], v[50:51] op_sel_hi:[1,0]
	v_pk_mul_f32 v[44:45], v[28:29], v[50:51] op_sel_hi:[1,0]
	v_pk_mul_f32 v[42:43], v[26:27], v[50:51] op_sel_hi:[1,0]
	v_pk_mul_f32 v[40:41], v[24:25], v[50:51] op_sel_hi:[1,0]
	v_pk_mul_f32 v[38:39], v[22:23], v[50:51] op_sel_hi:[1,0]
	v_pk_mul_f32 v[36:37], v[20:21], v[50:51] op_sel_hi:[1,0]
	v_pk_mul_f32 v[34:35], v[18:19], v[50:51] op_sel_hi:[1,0]
	v_pk_mul_f32 v[64:65], v[16:17], v[50:51] op_sel_hi:[1,0]
	v_pk_mul_f32 v[62:63], v[14:15], v[50:51] op_sel_hi:[1,0]
	v_pk_mul_f32 v[60:61], v[12:13], v[50:51] op_sel_hi:[1,0]
	v_pk_mul_f32 v[58:59], v[10:11], v[50:51] op_sel_hi:[1,0]
	v_pk_mul_f32 v[56:57], v[8:9], v[50:51] op_sel_hi:[1,0]
	v_pk_mul_f32 v[54:55], v[6:7], v[50:51] op_sel_hi:[1,0]
	v_pk_mul_f32 v[52:53], v[4:5], v[50:51] op_sel_hi:[1,0]
	v_pk_mul_f32 v[50:51], v[2:3], v[50:51] op_sel_hi:[1,0]
	v_cvt_pk_bf16_f32 v142, v142, v66
	v_add3_u32 v66, s81, v134, v101
	v_cvt_pk_bf16_f32 v144, v87, v88
	v_cvt_pk_bf16_f32 v145, v89, v146
	v_cvt_pk_bf16_f32 v88, v165, v84
	v_cvt_pk_bf16_f32 v89, v170, v90
	v_cvt_pk_bf16_f32 v90, v91, v150
	v_cvt_pk_bf16_f32 v91, v151, v152
	v_cvt_pk_bf16_f32 v84, v153, v154
	v_add3_u32 v154, s81, v135, v101
	ds_read_b64_tr_b16 v[150:151], v66
	v_add3_u32 v66, s81, v133, v101
	v_cvt_pk_bf16_f32 v143, v85, v86
	v_cvt_pk_bf16_f32 v85, v155, v158
	ds_read_b64_tr_b16 v[152:153], v66
	ds_read_b64_tr_b16 v[154:155], v154
	v_add3_u32 v66, s81, v132, v101
	v_cvt_pk_bf16_f32 v146, v147, v148
	v_cvt_pk_bf16_f32 v147, v149, v156
	v_cvt_pk_bf16_f32 v148, v157, v160
	ds_read_b64_tr_b16 v[156:157], v66
	v_add3_u32 v66, s81, v129, v101
	s_waitcnt lgkmcnt(2)
	v_mfma_f32_32x32x16_bf16 v[34:49], v[150:153], v[142:145], v[34:49]
	v_cvt_pk_bf16_f32 v149, v161, v166
	v_cvt_pk_bf16_f32 v86, v159, v162
	v_cvt_pk_bf16_f32 v87, v163, v168
	s_mov_b64 s[74:75], 0
	s_waitcnt lgkmcnt(0)
	v_mfma_f32_32x32x16_bf16 v[50:65], v[154:157], v[142:145], v[50:65]
	ds_read_b64_tr_b16 v[142:143], v66
	v_add3_u32 v66, s81, v128, v101
	ds_read_b64_tr_b16 v[144:145], v66
	v_add3_u32 v66, s81, v127, v101
	ds_read_b64_tr_b16 v[150:151], v66
	v_add3_u32 v66, s81, v126, v101
	ds_read_b64_tr_b16 v[152:153], v66
	v_add3_u32 v66, s81, v125, v101
	s_waitcnt lgkmcnt(2)
	v_mfma_f32_32x32x16_bf16 v[34:49], v[142:145], v[146:149], v[34:49]
	ds_read_b64_tr_b16 v[142:143], v66
	v_add3_u32 v66, s81, v124, v101
	ds_read_b64_tr_b16 v[144:145], v66
	v_add3_u32 v66, s81, v123, v101
	s_waitcnt lgkmcnt(2)
	v_mfma_f32_32x32x16_bf16 v[50:65], v[150:153], v[146:149], v[50:65]
	ds_read_b64_tr_b16 v[146:147], v66
	v_add3_u32 v66, s81, v122, v101
	ds_read_b64_tr_b16 v[148:149], v66
	v_add3_u32 v66, s81, v121, v101
	s_waitcnt lgkmcnt(2)
	v_mfma_f32_32x32x16_bf16 v[34:49], v[142:145], v[88:91], v[34:49]
	s_waitcnt lgkmcnt(0)
	v_mfma_f32_32x32x16_bf16 v[50:65], v[146:149], v[88:91], v[50:65]
	ds_read_b64_tr_b16 v[88:89], v66
	v_add3_u32 v66, s81, v120, v101
	ds_read_b64_tr_b16 v[90:91], v66
	v_add3_u32 v66, s81, v119, v101
	ds_read_b64_tr_b16 v[142:143], v66
	v_add3_u32 v66, s81, v118, v101
	ds_read_b64_tr_b16 v[144:145], v66
	s_waitcnt lgkmcnt(2)
	v_mfma_f32_32x32x16_bf16 v[34:49], v[88:91], v[84:87], v[34:49]
	s_waitcnt lgkmcnt(0)
	v_mfma_f32_32x32x16_bf16 v[50:65], v[142:145], v[84:87], v[50:65]
